# GEMM k-loops (in-proj, q/kv-up, MLP-up): in the first iteration of a tile that follows an epilogue the first two DMA waits are vmcnt(24) instead of vmcnt(8), so they no longer wait for the previous ti
# baseline (speedup 1.0000x reference)
.LBB0_287:
	v_lshrrev_b32_e32 v16, 1, v6
	v_and_b32_e32 v16, 24, v16
	v_and_b32_e32 v7, 15, v6
	v_lshlrev_b32_e32 v17, 1, v16
	v_lshlrev_b32_e32 v6, 2, v6
	s_lshl_b32 s1, s1, 5
	v_lshl_or_b32 v142, s10, 6, v7
	v_lshl_or_b32 v7, v7, 6, v17
	s_lshl_b32 s10, s10, 13
	v_and_b32_e32 v6, 32, v6
	s_and_b32 s1, s1, 0x60
	v_lshl_add_u64 v[8:9], s[8:9], 0, v[160:161]
	v_mov_b32_e32 v129, v161
	v_readlane_b32 s30, v246, 0
	v_bitop3_b32 v17, v7, s10, v6 bitop3:0xde
	s_lshl_b32 s10, s1, 7
	v_lshl_add_u64 v[10:11], s[8:9], 0, v[128:129]
	v_mov_b32_e32 v133, v161
	v_readlane_b32 s31, v246, 1
	v_bitop3_b32 v143, v7, s10, v6 bitop3:0xde
	s_add_i32 m0, s15, 0x18000
	v_lshl_add_u64 v[6:7], v[8:9], 0, s[64:65]
	v_lshl_add_u64 v[12:13], s[30:31], 0, v[132:133]
	v_mov_b32_e32 v131, v161
	s_waitcnt vmcnt(2)
	s_barrier
	global_load_lds_dwordx4 v[6:7], off
	v_lshl_add_u64 v[6:7], v[10:11], 0, s[64:65]
	s_add_i32 m0, s15, 0x1a000
	s_add_i32 s50, s15, 0x8000
	s_add_i32 s51, s15, 0xa000
	v_lshl_add_u64 v[14:15], s[30:31], 0, v[130:131]
	global_load_lds_dwordx4 v[6:7], off
	v_lshl_add_u64 v[6:7], v[12:13], 0, s[64:65]
	s_mov_b32 m0, s50
	s_add_u32 s10, s8, 0x80080
	global_load_lds_dwordx4 v[6:7], off
	v_lshl_add_u64 v[6:7], v[14:15], 0, s[64:65]
	s_mov_b32 m0, s51
	s_addc_u32 s11, s9, 0
	global_load_lds_dwordx4 v[6:7], off
	s_add_i32 m0, s15, 0x1c000
	v_lshl_add_u64 v[6:7], s[10:11], 0, v[160:161]
	global_load_lds_dwordx4 v[6:7], off
	v_lshl_add_u64 v[6:7], s[10:11], 0, v[128:129]
	s_add_i32 m0, s15, 0x1e000
	s_cmpk_lt_u32 s0, 0x100
	global_load_lds_dwordx4 v[6:7], off
	v_lshlrev_b32_e32 v6, 15, v4
	v_and_b32_e32 v6, 0xffff0000, v6
	v_lshl_add_u32 v3, v3, 12, v6
	v_and_b32_e32 v4, 1, v4
	v_lshl_or_b32 v3, v4, 6, v3
	v_lshl_add_u32 v134, v5, 1, v3
	v_lshlrev_b32_e32 v3, 15, v0
	v_and_b32_e32 v3, 0xffff0000, v3
	s_waitcnt vmcnt(6)
	v_lshl_add_u32 v1, v1, 12, v3
	v_and_b32_e32 v0, 1, v0
	v_lshl_or_b32 v0, v0, 6, v1
	v_readlane_b32 s0, v247, 63
	s_cselect_b64 s[10:11], -1, 0
	v_or_b32_e32 v144, s1, v16
	v_mov_b32_e32 v135, v161
	v_lshl_add_u32 v136, v2, 1, v0
	v_mov_b32_e32 v137, v161
	s_mov_b32 s58, 0
	v_add_u32_e32 v145, 0, v17
	v_readlane_b32 s16, v247, 61
	s_mov_b32 s12, s0
	s_barrier
	v_readlane_b32 s17, v247, 62
	s_mov_b32 s95, 0
	s_branch .LBB0_290
.LBB0_288:
	s_mov_b32 s95, 1
	s_mov_b64 s[0:1], 0

.LBB0_291:
	s_add_u32 s18, s54, 0xfff80080
	s_addc_u32 s19, s55, -1
	s_add_i32 s66, 0, 0x10000
	s_cmp_eq_u32 s63, 28
	s_cselect_b32 s21, s17, s19
	s_cselect_b32 s20, s59, s18
	s_cselect_b32 s19, s13, s62
	s_cselect_b32 s18, s60, s61
	s_add_i32 s68, 0, 0x14000
	v_add_u32_e32 v154, s66, v143
	v_add_u32_e32 v158, s68, v143
	ds_read_b128 v[138:141], v154
	ds_read_b128 v[146:149], v154 offset:1024
	ds_read_b128 v[150:153], v154 offset:2048
	ds_read_b128 v[154:157], v154 offset:3072
	ds_read_b128 v[162:165], v158
	ds_read_b128 v[166:169], v158 offset:1024
	ds_read_b128 v[182:185], v158 offset:2048
	ds_read_b128 v[186:189], v158 offset:3072
	v_lshl_add_u64 v[158:159], s[54:55], 0, v[134:135]
	s_add_i32 m0, s15, 0xc000
	ds_read_b128 v[190:193], v145
	ds_read_b128 v[194:197], v145 offset:1024
	ds_read_b128 v[198:201], v145 offset:2048
	ds_read_b128 v[202:205], v145 offset:3072
	ds_read_b128 v[206:209], v145 offset:4096
	ds_read_b128 v[210:213], v145 offset:5120
	ds_read_b128 v[214:217], v145 offset:6144
	ds_read_b128 v[218:221], v145 offset:7168
	global_load_lds_dwordx4 v[158:159], off
	v_lshl_add_u64 v[158:159], s[54:55], 0, v[136:137]
	s_add_i32 m0, s15, 0xe000
	s_nop 0
	global_load_lds_dwordx4 v[158:159], off
	s_cmp_lg_u32 s95, 0
	s_cbranch_scc1 .Lst_ip_r0
	s_waitcnt vmcnt(8)
.Lst_ip_d0:
	s_waitcnt lgkmcnt(0)
	s_barrier
	s_setprio 1
	s_waitcnt lgkmcnt(0)
	v_mfma_f32_16x16x32_bf16 v[124:127], v[138:141], v[190:193], v[124:127]
	v_mfma_f32_16x16x32_bf16 v[120:123], v[150:153], v[190:193], v[120:123]
	v_mfma_f32_16x16x32_bf16 v[116:119], v[138:141], v[198:201], v[116:119]
	v_mfma_f32_16x16x32_bf16 v[108:111], v[150:153], v[198:201], v[108:111]
	v_mfma_f32_16x16x32_bf16 v[100:103], v[138:141], v[206:209], v[100:103]
	v_mfma_f32_16x16x32_bf16 v[92:95], v[150:153], v[206:209], v[92:95]
	v_mfma_f32_16x16x32_bf16 v[84:87], v[138:141], v[214:217], v[84:87]
	v_mfma_f32_16x16x32_bf16 v[76:79], v[150:153], v[214:217], v[76:79]
	v_mfma_f32_16x16x32_bf16 v[124:127], v[146:149], v[194:197], v[124:127]
	v_mfma_f32_16x16x32_bf16 v[120:123], v[154:157], v[194:197], v[120:123]
	v_mfma_f32_16x16x32_bf16 v[116:119], v[146:149], v[202:205], v[116:119]
	v_mfma_f32_16x16x32_bf16 v[108:111], v[154:157], v[202:205], v[108:111]
	v_mfma_f32_16x16x32_bf16 v[100:103], v[146:149], v[210:213], v[100:103]
	v_mfma_f32_16x16x32_bf16 v[92:95], v[154:157], v[210:213], v[92:95]
	v_mfma_f32_16x16x32_bf16 v[84:87], v[146:149], v[218:221], v[84:87]
	v_mfma_f32_16x16x32_bf16 v[76:79], v[154:157], v[218:221], v[76:79]
	s_setprio 0
	s_setprio 1
	v_mfma_f32_16x16x32_bf16 v[112:115], v[162:165], v[190:193], v[112:115]
	v_mfma_f32_16x16x32_bf16 v[104:107], v[182:185], v[190:193], v[104:107]
	v_mfma_f32_16x16x32_bf16 v[96:99], v[162:165], v[198:201], v[96:99]
	v_mfma_f32_16x16x32_bf16 v[88:91], v[182:185], v[198:201], v[88:91]
	v_mfma_f32_16x16x32_bf16 v[80:83], v[162:165], v[206:209], v[80:83]
	v_mfma_f32_16x16x32_bf16 v[72:75], v[182:185], v[206:209], v[72:75]
	v_mfma_f32_16x16x32_bf16 v[68:71], v[162:165], v[214:217], v[68:71]
	v_mfma_f32_16x16x32_bf16 v[64:67], v[182:185], v[214:217], v[64:67]
	v_mfma_f32_16x16x32_bf16 v[112:115], v[166:169], v[194:197], v[112:115]
	v_mfma_f32_16x16x32_bf16 v[104:107], v[186:189], v[194:197], v[104:107]
	v_mfma_f32_16x16x32_bf16 v[96:99], v[166:169], v[202:205], v[96:99]
	v_mfma_f32_16x16x32_bf16 v[88:91], v[186:189], v[202:205], v[88:91]
	v_mfma_f32_16x16x32_bf16 v[80:83], v[166:169], v[210:213], v[80:83]
	v_mfma_f32_16x16x32_bf16 v[72:75], v[186:189], v[210:213], v[72:75]
	v_mfma_f32_16x16x32_bf16 v[68:71], v[166:169], v[218:221], v[68:71]
	v_mfma_f32_16x16x32_bf16 v[64:67], v[186:189], v[218:221], v[64:67]
	s_setprio 0
	s_barrier
	s_add_i32 s66, s66, s14
	v_lshl_add_u64 v[158:159], s[18:19], 0, v[160:161]
	s_mov_b32 m0, s66
	ds_read_b128 v[190:193], v145 offset:16384
	ds_read_b128 v[194:197], v145 offset:17408
	ds_read_b128 v[198:201], v145 offset:18432
	ds_read_b128 v[202:205], v145 offset:19456
	ds_read_b128 v[206:209], v145 offset:20480
	ds_read_b128 v[210:213], v145 offset:21504
	ds_read_b128 v[214:217], v145 offset:22528
	ds_read_b128 v[218:221], v145 offset:23552
	global_load_lds_dwordx4 v[158:159], off
	s_add_i32 m0, s66, 0x2000
	s_add_u32 s66, s18, 0x80000
	v_lshl_add_u64 v[170:171], s[18:19], 0, v[128:129]
	s_addc_u32 s67, s19, 0
	s_add_i32 s68, s68, s14
	global_load_lds_dwordx4 v[170:171], off
	v_lshl_add_u64 v[222:223], s[66:67], 0, v[160:161]
	s_mov_b32 m0, s68
	v_lshl_add_u64 v[224:225], s[20:21], 0, v[130:131]
	global_load_lds_dwordx4 v[222:223], off
	v_lshl_add_u64 v[222:223], s[66:67], 0, v[128:129]
	s_add_i32 m0, s68, 0x2000
	s_nop 0
	global_load_lds_dwordx4 v[222:223], off
	v_lshl_add_u64 v[222:223], s[20:21], 0, v[132:133]
	s_mov_b32 m0, s15
	s_nop 0
	global_load_lds_dwordx4 v[222:223], off
	s_mov_b32 m0, s44
	s_nop 0
	global_load_lds_dwordx4 v[224:225], off
	s_cmp_lg_u32 s95, 0
	s_cbranch_scc1 .Lst_ip_r1
	s_waitcnt vmcnt(8)
.Lst_ip_d1:
	s_waitcnt lgkmcnt(0)
	s_barrier
	s_setprio 1
	s_waitcnt lgkmcnt(0)
	v_mfma_f32_16x16x32_bf16 v[60:63], v[138:141], v[190:193], v[60:63]
	v_mfma_f32_16x16x32_bf16 v[56:59], v[150:153], v[190:193], v[56:59]
	v_mfma_f32_16x16x32_bf16 v[52:55], v[138:141], v[198:201], v[52:55]
	v_mfma_f32_16x16x32_bf16 v[44:47], v[150:153], v[198:201], v[44:47]
	v_mfma_f32_16x16x32_bf16 v[36:39], v[138:141], v[206:209], v[36:39]
	v_mfma_f32_16x16x32_bf16 v[28:31], v[150:153], v[206:209], v[28:31]
	v_mfma_f32_16x16x32_bf16 v[20:23], v[138:141], v[214:217], v[20:23]
	v_mfma_f32_16x16x32_bf16 v[12:15], v[150:153], v[214:217], v[12:15]
	v_mfma_f32_16x16x32_bf16 v[60:63], v[146:149], v[194:197], v[60:63]
	v_mfma_f32_16x16x32_bf16 v[56:59], v[154:157], v[194:197], v[56:59]
	v_mfma_f32_16x16x32_bf16 v[52:55], v[146:149], v[202:205], v[52:55]
	v_mfma_f32_16x16x32_bf16 v[44:47], v[154:157], v[202:205], v[44:47]
	v_mfma_f32_16x16x32_bf16 v[36:39], v[146:149], v[210:213], v[36:39]
	v_mfma_f32_16x16x32_bf16 v[28:31], v[154:157], v[210:213], v[28:31]
	v_mfma_f32_16x16x32_bf16 v[20:23], v[146:149], v[218:221], v[20:23]
	v_mfma_f32_16x16x32_bf16 v[12:15], v[154:157], v[218:221], v[12:15]
	s_setprio 0
	s_setprio 1
	v_mfma_f32_16x16x32_bf16 v[48:51], v[162:165], v[190:193], v[48:51]
	v_mfma_f32_16x16x32_bf16 v[40:43], v[182:185], v[190:193], v[40:43]
	v_mfma_f32_16x16x32_bf16 v[32:35], v[162:165], v[198:201], v[32:35]
	v_mfma_f32_16x16x32_bf16 v[24:27], v[182:185], v[198:201], v[24:27]
	v_mfma_f32_16x16x32_bf16 v[16:19], v[162:165], v[206:209], v[16:19]
	v_mfma_f32_16x16x32_bf16 v[8:11], v[182:185], v[206:209], v[8:11]
	v_mfma_f32_16x16x32_bf16 v[4:7], v[162:165], v[214:217], v[4:7]
	v_mfma_f32_16x16x32_bf16 v[0:3], v[182:185], v[214:217], v[0:3]
	v_mfma_f32_16x16x32_bf16 v[48:51], v[166:169], v[194:197], v[48:51]
	v_mfma_f32_16x16x32_bf16 v[40:43], v[186:189], v[194:197], v[40:43]
	v_mfma_f32_16x16x32_bf16 v[32:35], v[166:169], v[202:205], v[32:35]
	v_mfma_f32_16x16x32_bf16 v[24:27], v[186:189], v[202:205], v[24:27]
	v_mfma_f32_16x16x32_bf16 v[16:19], v[166:169], v[210:213], v[16:19]
	v_mfma_f32_16x16x32_bf16 v[8:11], v[186:189], v[210:213], v[8:11]
	v_mfma_f32_16x16x32_bf16 v[4:7], v[166:169], v[218:221], v[4:7]
	v_mfma_f32_16x16x32_bf16 v[0:3], v[186:189], v[218:221], v[0:3]
	s_setprio 0
	s_barrier
	s_add_i32 s66, 0, 0x18000
	s_add_i32 s67, 0, 0x1c000
	v_add_u32_e32 v154, s66, v143
	v_add_u32_e32 v181, s67, v143
	ds_read_b128 v[138:141], v154
	ds_read_b128 v[146:149], v154 offset:1024
	ds_read_b128 v[150:153], v154 offset:2048
	ds_read_b128 v[154:157], v154 offset:3072
	ds_read_b128 v[162:165], v181
	ds_read_b128 v[166:169], v181 offset:1024
	ds_read_b128 v[182:185], v181 offset:2048
	ds_read_b128 v[186:189], v181 offset:3072
	s_add_u32 s20, s20, 0x80000
	s_addc_u32 s21, s21, 0
	s_mov_b32 m0, s45
	v_lshl_add_u64 v[226:227], s[20:21], 0, v[132:133]
	ds_read_b128 v[190:193], v145 offset:32768
	ds_read_b128 v[194:197], v145 offset:33792
	ds_read_b128 v[198:201], v145 offset:34816
	ds_read_b128 v[202:205], v145 offset:35840
	ds_read_b128 v[206:209], v145 offset:36864
	ds_read_b128 v[210:213], v145 offset:37888
	ds_read_b128 v[214:217], v145 offset:38912
	ds_read_b128 v[218:221], v145 offset:39936
	global_load_lds_dwordx4 v[226:227], off
	v_lshl_add_u64 v[226:227], s[20:21], 0, v[130:131]
	s_mov_b32 m0, s49
	s_nop 0
	global_load_lds_dwordx4 v[226:227], off
	s_waitcnt vmcnt(8)
	s_waitcnt lgkmcnt(0)
	s_barrier
	s_setprio 1
	s_waitcnt lgkmcnt(0)
	v_mfma_f32_16x16x32_bf16 v[124:127], v[138:141], v[190:193], v[124:127]
	v_mfma_f32_16x16x32_bf16 v[120:123], v[150:153], v[190:193], v[120:123]
	v_mfma_f32_16x16x32_bf16 v[116:119], v[138:141], v[198:201], v[116:119]
	v_mfma_f32_16x16x32_bf16 v[108:111], v[150:153], v[198:201], v[108:111]
	v_mfma_f32_16x16x32_bf16 v[100:103], v[138:141], v[206:209], v[100:103]
	v_mfma_f32_16x16x32_bf16 v[92:95], v[150:153], v[206:209], v[92:95]
	v_mfma_f32_16x16x32_bf16 v[84:87], v[138:141], v[214:217], v[84:87]
	v_mfma_f32_16x16x32_bf16 v[76:79], v[150:153], v[214:217], v[76:79]
	v_mfma_f32_16x16x32_bf16 v[124:127], v[146:149], v[194:197], v[124:127]
	v_mfma_f32_16x16x32_bf16 v[120:123], v[154:157], v[194:197], v[120:123]
	v_mfma_f32_16x16x32_bf16 v[116:119], v[146:149], v[202:205], v[116:119]
	v_mfma_f32_16x16x32_bf16 v[108:111], v[154:157], v[202:205], v[108:111]
	v_mfma_f32_16x16x32_bf16 v[100:103], v[146:149], v[210:213], v[100:103]
	v_mfma_f32_16x16x32_bf16 v[92:95], v[154:157], v[210:213], v[92:95]
	v_mfma_f32_16x16x32_bf16 v[84:87], v[146:149], v[218:221], v[84:87]
	v_mfma_f32_16x16x32_bf16 v[76:79], v[154:157], v[218:221], v[76:79]
	s_setprio 0
	s_setprio 1
	v_mfma_f32_16x16x32_bf16 v[112:115], v[162:165], v[190:193], v[112:115]
	v_mfma_f32_16x16x32_bf16 v[104:107], v[182:185], v[190:193], v[104:107]
	v_mfma_f32_16x16x32_bf16 v[96:99], v[162:165], v[198:201], v[96:99]
	v_mfma_f32_16x16x32_bf16 v[88:91], v[182:185], v[198:201], v[88:91]
	v_mfma_f32_16x16x32_bf16 v[80:83], v[162:165], v[206:209], v[80:83]
	v_mfma_f32_16x16x32_bf16 v[72:75], v[182:185], v[206:209], v[72:75]
	v_mfma_f32_16x16x32_bf16 v[68:71], v[162:165], v[214:217], v[68:71]
	v_mfma_f32_16x16x32_bf16 v[64:67], v[182:185], v[214:217], v[64:67]
	v_mfma_f32_16x16x32_bf16 v[112:115], v[166:169], v[194:197], v[112:115]
	v_mfma_f32_16x16x32_bf16 v[104:107], v[186:189], v[194:197], v[104:107]
	v_mfma_f32_16x16x32_bf16 v[96:99], v[166:169], v[202:205], v[96:99]
	v_mfma_f32_16x16x32_bf16 v[88:91], v[186:189], v[202:205], v[88:91]
	v_mfma_f32_16x16x32_bf16 v[80:83], v[166:169], v[210:213], v[80:83]
	v_mfma_f32_16x16x32_bf16 v[72:75], v[186:189], v[210:213], v[72:75]
	v_mfma_f32_16x16x32_bf16 v[68:71], v[166:169], v[218:221], v[68:71]
	v_mfma_f32_16x16x32_bf16 v[64:67], v[186:189], v[218:221], v[64:67]
	s_setprio 0
	s_barrier
	s_add_i32 s20, s66, s14
	v_lshl_add_u64 v[158:159], v[158:159], 0, s[64:65]
	s_mov_b32 m0, s20
	ds_read_b128 v[190:193], v145 offset:49152
	ds_read_b128 v[194:197], v145 offset:50176
	ds_read_b128 v[198:201], v145 offset:51200
	ds_read_b128 v[202:205], v145 offset:52224
	ds_read_b128 v[206:209], v145 offset:53248
	ds_read_b128 v[210:213], v145 offset:54272
	ds_read_b128 v[214:217], v145 offset:55296
	ds_read_b128 v[218:221], v145 offset:56320
	global_load_lds_dwordx4 v[158:159], off
	s_add_i32 m0, s20, 0x2000
	s_add_u32 s18, s18, 0x80080
	v_lshl_add_u64 v[158:159], v[170:171], 0, s[64:65]
	s_addc_u32 s19, s19, 0
	s_add_i32 s20, s67, s14
	global_load_lds_dwordx4 v[158:159], off
	v_lshl_add_u64 v[158:159], s[18:19], 0, v[160:161]
	s_mov_b32 m0, s20
	s_nop 0
	global_load_lds_dwordx4 v[158:159], off
	v_lshl_add_u64 v[158:159], s[18:19], 0, v[128:129]
	s_add_i32 m0, s20, 0x2000
	s_nop 0
	global_load_lds_dwordx4 v[158:159], off
	v_lshl_add_u64 v[158:159], v[222:223], 0, s[64:65]
	s_mov_b32 m0, s50
	s_nop 0
	global_load_lds_dwordx4 v[158:159], off
	v_lshl_add_u64 v[158:159], v[224:225], 0, s[64:65]
	s_mov_b32 m0, s51
	s_nop 0
	global_load_lds_dwordx4 v[158:159], off
	s_waitcnt vmcnt(8)
	s_waitcnt lgkmcnt(0)
	s_barrier
	s_setprio 1
	s_waitcnt lgkmcnt(0)
	v_mfma_f32_16x16x32_bf16 v[60:63], v[138:141], v[190:193], v[60:63]
	v_mfma_f32_16x16x32_bf16 v[56:59], v[150:153], v[190:193], v[56:59]
	v_mfma_f32_16x16x32_bf16 v[52:55], v[138:141], v[198:201], v[52:55]
	v_mfma_f32_16x16x32_bf16 v[44:47], v[150:153], v[198:201], v[44:47]
	v_mfma_f32_16x16x32_bf16 v[36:39], v[138:141], v[206:209], v[36:39]
	v_mfma_f32_16x16x32_bf16 v[28:31], v[150:153], v[206:209], v[28:31]
	v_mfma_f32_16x16x32_bf16 v[20:23], v[138:141], v[214:217], v[20:23]
	v_mfma_f32_16x16x32_bf16 v[12:15], v[150:153], v[214:217], v[12:15]
	v_mfma_f32_16x16x32_bf16 v[60:63], v[146:149], v[194:197], v[60:63]
	v_mfma_f32_16x16x32_bf16 v[56:59], v[154:157], v[194:197], v[56:59]
	v_mfma_f32_16x16x32_bf16 v[52:55], v[146:149], v[202:205], v[52:55]
	v_mfma_f32_16x16x32_bf16 v[44:47], v[154:157], v[202:205], v[44:47]
	v_mfma_f32_16x16x32_bf16 v[36:39], v[146:149], v[210:213], v[36:39]
	v_mfma_f32_16x16x32_bf16 v[28:31], v[154:157], v[210:213], v[28:31]
	v_mfma_f32_16x16x32_bf16 v[20:23], v[146:149], v[218:221], v[20:23]
	v_mfma_f32_16x16x32_bf16 v[12:15], v[154:157], v[218:221], v[12:15]
	s_setprio 0
	s_setprio 1
	v_mfma_f32_16x16x32_bf16 v[48:51], v[162:165], v[190:193], v[48:51]
	v_mfma_f32_16x16x32_bf16 v[40:43], v[182:185], v[190:193], v[40:43]
	v_mfma_f32_16x16x32_bf16 v[32:35], v[162:165], v[198:201], v[32:35]
	v_mfma_f32_16x16x32_bf16 v[24:27], v[182:185], v[198:201], v[24:27]
	v_mfma_f32_16x16x32_bf16 v[16:19], v[162:165], v[206:209], v[16:19]
	v_mfma_f32_16x16x32_bf16 v[8:11], v[182:185], v[206:209], v[8:11]
	v_mfma_f32_16x16x32_bf16 v[4:7], v[162:165], v[214:217], v[4:7]
	v_mfma_f32_16x16x32_bf16 v[0:3], v[182:185], v[214:217], v[0:3]
	v_mfma_f32_16x16x32_bf16 v[48:51], v[166:169], v[194:197], v[48:51]
	v_mfma_f32_16x16x32_bf16 v[40:43], v[186:189], v[194:197], v[40:43]
	v_mfma_f32_16x16x32_bf16 v[32:35], v[166:169], v[202:205], v[32:35]
	v_mfma_f32_16x16x32_bf16 v[24:27], v[186:189], v[202:205], v[24:27]
	v_mfma_f32_16x16x32_bf16 v[16:19], v[166:169], v[210:213], v[16:19]
	v_mfma_f32_16x16x32_bf16 v[8:11], v[186:189], v[210:213], v[8:11]
	v_mfma_f32_16x16x32_bf16 v[4:7], v[166:169], v[218:221], v[4:7]
	v_mfma_f32_16x16x32_bf16 v[0:3], v[186:189], v[218:221], v[0:3]
	s_setprio 0
	s_barrier
	s_add_i32 s63, s63, 2
	s_add_u32 s54, s54, 0x100
	s_addc_u32 s55, s55, 0
	s_add_u32 s61, s61, 0x100
	s_addc_u32 s62, s62, 0
	s_mov_b32 s95, 0
	s_cmp_gt_u32 s63, 29
	s_cbranch_scc0 .LBB0_291
	s_branch .Lst_ip_after
.Lst_ip_r0:
	s_waitcnt vmcnt(24)
	s_branch .Lst_ip_d0

.Lst_ip_after:
	s_and_b64 vcc, exec, s[10:11]
	s_cbranch_vccz .LBB0_294
	s_barrier

.LBB0_465:
	s_and_b64 s[10:11], s[6:7], exec
	v_lshrrev_b32_e32 v18, 1, v8
	v_readlane_b32 s1, v248, 56
	v_readlane_b32 s10, v248, 58
	v_and_b32_e32 v18, 24, v18
	s_cselect_b32 s11, s1, s10
	v_readlane_b32 s1, v248, 55
	v_readlane_b32 s10, v248, 57
	v_and_b32_e32 v17, 15, v8
	v_lshlrev_b32_e32 v19, 1, v18
	v_lshlrev_b32_e32 v8, 2, v8
	s_cselect_b32 s10, s1, s10
	v_lshl_or_b32 v140, s16, 6, v17
	v_lshl_or_b32 v17, v17, 6, v19
	s_lshl_b32 s1, s16, 13
	v_and_b32_e32 v8, 32, v8
	v_bitop3_b32 v19, v17, s1, v8 bitop3:0xde
	s_lshl_b32 s1, s13, 5
	s_and_b32 s1, s1, 0x60
	s_add_i32 m0, s31, 0x18000
	v_lshl_add_u64 v[6:7], v[6:7], 0, s[64:65]
	s_lshl_b32 s13, s1, 7
	s_waitcnt vmcnt(2)
	s_barrier
	global_load_lds_dwordx4 v[6:7], off
	v_lshl_add_u64 v[4:5], v[4:5], 0, s[64:65]
	s_add_i32 m0, s31, 0x1a000
	s_add_i32 s76, s31, 0x8000
	s_add_i32 s77, s31, 0xa000
	global_load_lds_dwordx4 v[4:5], off
	v_lshl_add_u64 v[0:1], v[0:1], 0, s[64:65]
	s_mov_b32 m0, s76
	s_add_u32 s16, s18, 0x20080
	global_load_lds_dwordx4 v[0:1], off
	v_lshl_add_u64 v[0:1], v[2:3], 0, s[64:65]
	s_mov_b32 m0, s77
	s_addc_u32 s17, s19, 0
	global_load_lds_dwordx4 v[0:1], off
	s_add_i32 m0, s31, 0x1c000
	v_lshl_add_u64 v[0:1], s[16:17], 0, v[160:161]
	global_load_lds_dwordx4 v[0:1], off
	v_lshl_add_u64 v[0:1], s[16:17], 0, v[128:129]
	s_add_i32 m0, s31, 0x1e000
	v_or_b32_e32 v142, s1, v18
	global_load_lds_dwordx4 v[0:1], off
	v_lshrrev_b32_e32 v1, 1, v14
	v_mul_lo_u32 v0, v13, s38
	s_mov_b32 s1, 0xc000
	v_mad_u64_u32 v[0:1], s[16:17], v1, s1, v[0:1]
	v_or_b32_e32 v0, v0, v15
	v_add_lshl_u32 v0, v0, v16, 1
	v_mov_b32_e32 v1, v161
	s_mov_b64 s[20:21], 0xc0080
	v_lshl_add_u64 v[134:135], v[0:1], 0, s[20:21]
	v_lshrrev_b32_e32 v1, 1, v9
	v_mul_lo_u32 v0, v10, s38
	v_mad_u64_u32 v[0:1], s[16:17], v1, s1, v[0:1]
	s_waitcnt vmcnt(6)
	v_or_b32_e32 v0, v0, v11
	s_cmpk_lt_u32 s12, 0x100
	v_add_lshl_u32 v0, v0, v12, 1
	v_mov_b32_e32 v1, v161
	v_bitop3_b32 v141, v17, s13, v8 bitop3:0xde
	s_cselect_b64 s[12:13], -1, 0
	v_lshl_add_u64 v[136:137], v[0:1], 0, s[20:21]
	s_mov_b32 s78, 0
	v_add_u32_e32 v143, 0, v19
	s_mov_b64 s[16:17], s[72:73]
	s_barrier
	s_mov_b32 s95, 0
	s_branch .LBB0_468

.LBB0_471:
	s_add_u32 s18, s72, 0x100
	s_addc_u32 s19, s73, 0
	s_add_i32 s83, 0, 0x10000
	s_cmp_eq_u32 s82, 4
	s_cselect_b32 s45, s17, s19
	s_cselect_b32 s44, s16, s18
	v_add_u32_e32 v138, s83, v141
	s_cselect_b32 s21, s1, s81
	s_cselect_b32 s20, s55, s80
	s_add_i32 s84, 0, 0x14000
	ds_read_b128 v[144:147], v138
	ds_read_b128 v[148:151], v138 offset:1024
	ds_read_b128 v[152:155], v138 offset:2048
	ds_read_b128 v[156:159], v138 offset:3072
	v_add_u32_e32 v138, s84, v141
	ds_read_b128 v[162:165], v138
	ds_read_b128 v[166:169], v138 offset:1024
	ds_read_b128 v[182:185], v138 offset:2048
	ds_read_b128 v[186:189], v138 offset:3072
	v_lshl_add_u64 v[138:139], s[72:73], 0, v[134:135]
	s_add_i32 m0, s31, 0xc000
	ds_read_b128 v[190:193], v143
	ds_read_b128 v[194:197], v143 offset:1024
	ds_read_b128 v[198:201], v143 offset:2048
	ds_read_b128 v[202:205], v143 offset:3072
	ds_read_b128 v[206:209], v143 offset:4096
	ds_read_b128 v[210:213], v143 offset:5120
	ds_read_b128 v[214:217], v143 offset:6144
	ds_read_b128 v[218:221], v143 offset:7168
	global_load_lds_dwordx4 v[138:139], off
	v_lshl_add_u64 v[138:139], s[72:73], 0, v[136:137]
	s_add_i32 m0, s31, 0xe000
	s_nop 0
	global_load_lds_dwordx4 v[138:139], off
	s_cmp_lg_u32 s95, 0
	s_cbranch_scc1 .Lst_qk_r0
	s_waitcnt vmcnt(8)
.Lst_qk_d0:
	s_waitcnt lgkmcnt(0)
	s_barrier
	s_setprio 1
	s_waitcnt lgkmcnt(0)
	v_mfma_f32_16x16x32_bf16 v[124:127], v[144:147], v[190:193], v[124:127]
	v_mfma_f32_16x16x32_bf16 v[120:123], v[152:155], v[190:193], v[120:123]
	v_mfma_f32_16x16x32_bf16 v[116:119], v[144:147], v[198:201], v[116:119]
	v_mfma_f32_16x16x32_bf16 v[108:111], v[152:155], v[198:201], v[108:111]
	v_mfma_f32_16x16x32_bf16 v[100:103], v[144:147], v[206:209], v[100:103]
	v_mfma_f32_16x16x32_bf16 v[92:95], v[152:155], v[206:209], v[92:95]
	v_mfma_f32_16x16x32_bf16 v[84:87], v[144:147], v[214:217], v[84:87]
	v_mfma_f32_16x16x32_bf16 v[76:79], v[152:155], v[214:217], v[76:79]
	v_mfma_f32_16x16x32_bf16 v[124:127], v[148:151], v[194:197], v[124:127]
	v_mfma_f32_16x16x32_bf16 v[120:123], v[156:159], v[194:197], v[120:123]
	v_mfma_f32_16x16x32_bf16 v[116:119], v[148:151], v[202:205], v[116:119]
	v_mfma_f32_16x16x32_bf16 v[108:111], v[156:159], v[202:205], v[108:111]
	v_mfma_f32_16x16x32_bf16 v[100:103], v[148:151], v[210:213], v[100:103]
	v_mfma_f32_16x16x32_bf16 v[92:95], v[156:159], v[210:213], v[92:95]
	v_mfma_f32_16x16x32_bf16 v[84:87], v[148:151], v[218:221], v[84:87]
	v_mfma_f32_16x16x32_bf16 v[76:79], v[156:159], v[218:221], v[76:79]
	s_setprio 0
	s_setprio 1
	v_mfma_f32_16x16x32_bf16 v[112:115], v[162:165], v[190:193], v[112:115]
	v_mfma_f32_16x16x32_bf16 v[104:107], v[182:185], v[190:193], v[104:107]
	v_mfma_f32_16x16x32_bf16 v[96:99], v[162:165], v[198:201], v[96:99]
	v_mfma_f32_16x16x32_bf16 v[88:91], v[182:185], v[198:201], v[88:91]
	v_mfma_f32_16x16x32_bf16 v[80:83], v[162:165], v[206:209], v[80:83]
	v_mfma_f32_16x16x32_bf16 v[72:75], v[182:185], v[206:209], v[72:75]
	v_mfma_f32_16x16x32_bf16 v[68:71], v[162:165], v[214:217], v[68:71]
	v_mfma_f32_16x16x32_bf16 v[64:67], v[182:185], v[214:217], v[64:67]
	v_mfma_f32_16x16x32_bf16 v[112:115], v[166:169], v[194:197], v[112:115]
	v_mfma_f32_16x16x32_bf16 v[104:107], v[186:189], v[194:197], v[104:107]
	v_mfma_f32_16x16x32_bf16 v[96:99], v[166:169], v[202:205], v[96:99]
	v_mfma_f32_16x16x32_bf16 v[88:91], v[186:189], v[202:205], v[88:91]
	v_mfma_f32_16x16x32_bf16 v[80:83], v[166:169], v[210:213], v[80:83]
	v_mfma_f32_16x16x32_bf16 v[72:75], v[186:189], v[210:213], v[72:75]
	v_mfma_f32_16x16x32_bf16 v[68:71], v[166:169], v[218:221], v[68:71]
	v_mfma_f32_16x16x32_bf16 v[64:67], v[186:189], v[218:221], v[64:67]
	s_setprio 0
	s_barrier
	s_add_i32 s72, s83, s61
	v_lshl_add_u64 v[138:139], s[20:21], 0, v[160:161]
	s_mov_b32 m0, s72
	ds_read_b128 v[190:193], v143 offset:16384
	ds_read_b128 v[194:197], v143 offset:17408
	ds_read_b128 v[198:201], v143 offset:18432
	ds_read_b128 v[202:205], v143 offset:19456
	ds_read_b128 v[206:209], v143 offset:20480
	ds_read_b128 v[210:213], v143 offset:21504
	ds_read_b128 v[214:217], v143 offset:22528
	ds_read_b128 v[218:221], v143 offset:23552
	global_load_lds_dwordx4 v[138:139], off
	s_add_i32 m0, s72, 0x2000
	s_add_u32 s72, s20, 0x20000
	v_lshl_add_u64 v[170:171], s[20:21], 0, v[128:129]
	s_addc_u32 s73, s21, 0
	s_add_i32 s83, s84, s61
	global_load_lds_dwordx4 v[170:171], off
	v_lshl_add_u64 v[222:223], s[72:73], 0, v[160:161]
	s_mov_b32 m0, s83
	v_lshl_add_u64 v[224:225], s[44:45], 0, v[130:131]
	global_load_lds_dwordx4 v[222:223], off
	v_lshl_add_u64 v[222:223], s[72:73], 0, v[128:129]
	s_add_i32 m0, s83, 0x2000
	s_nop 0
	global_load_lds_dwordx4 v[222:223], off
	v_lshl_add_u64 v[222:223], s[44:45], 0, v[132:133]
	s_mov_b32 m0, s31
	s_nop 0
	global_load_lds_dwordx4 v[222:223], off
	s_mov_b32 m0, s68
	s_nop 0
	global_load_lds_dwordx4 v[224:225], off
	s_cmp_lg_u32 s95, 0
	s_cbranch_scc1 .Lst_qk_r1
	s_waitcnt vmcnt(8)
.Lst_qk_d1:
	s_waitcnt lgkmcnt(0)
	s_barrier
	s_setprio 1
	s_waitcnt lgkmcnt(0)
	v_mfma_f32_16x16x32_bf16 v[60:63], v[144:147], v[190:193], v[60:63]
	v_mfma_f32_16x16x32_bf16 v[56:59], v[152:155], v[190:193], v[56:59]
	v_mfma_f32_16x16x32_bf16 v[52:55], v[144:147], v[198:201], v[52:55]
	v_mfma_f32_16x16x32_bf16 v[44:47], v[152:155], v[198:201], v[44:47]
	v_mfma_f32_16x16x32_bf16 v[36:39], v[144:147], v[206:209], v[36:39]
	v_mfma_f32_16x16x32_bf16 v[28:31], v[152:155], v[206:209], v[28:31]
	v_mfma_f32_16x16x32_bf16 v[20:23], v[144:147], v[214:217], v[20:23]
	v_mfma_f32_16x16x32_bf16 v[12:15], v[152:155], v[214:217], v[12:15]
	v_mfma_f32_16x16x32_bf16 v[60:63], v[148:151], v[194:197], v[60:63]
	v_mfma_f32_16x16x32_bf16 v[56:59], v[156:159], v[194:197], v[56:59]
	v_mfma_f32_16x16x32_bf16 v[52:55], v[148:151], v[202:205], v[52:55]
	v_mfma_f32_16x16x32_bf16 v[44:47], v[156:159], v[202:205], v[44:47]
	v_mfma_f32_16x16x32_bf16 v[36:39], v[148:151], v[210:213], v[36:39]
	v_mfma_f32_16x16x32_bf16 v[28:31], v[156:159], v[210:213], v[28:31]
	v_mfma_f32_16x16x32_bf16 v[20:23], v[148:151], v[218:221], v[20:23]
	v_mfma_f32_16x16x32_bf16 v[12:15], v[156:159], v[218:221], v[12:15]
	s_setprio 0
	s_setprio 1
	v_mfma_f32_16x16x32_bf16 v[48:51], v[162:165], v[190:193], v[48:51]
	v_mfma_f32_16x16x32_bf16 v[40:43], v[182:185], v[190:193], v[40:43]
	v_mfma_f32_16x16x32_bf16 v[32:35], v[162:165], v[198:201], v[32:35]
	v_mfma_f32_16x16x32_bf16 v[24:27], v[182:185], v[198:201], v[24:27]
	v_mfma_f32_16x16x32_bf16 v[16:19], v[162:165], v[206:209], v[16:19]
	v_mfma_f32_16x16x32_bf16 v[8:11], v[182:185], v[206:209], v[8:11]
	v_mfma_f32_16x16x32_bf16 v[4:7], v[162:165], v[214:217], v[4:7]
	v_mfma_f32_16x16x32_bf16 v[0:3], v[182:185], v[214:217], v[0:3]
	v_mfma_f32_16x16x32_bf16 v[48:51], v[166:169], v[194:197], v[48:51]
	v_mfma_f32_16x16x32_bf16 v[40:43], v[186:189], v[194:197], v[40:43]
	v_mfma_f32_16x16x32_bf16 v[32:35], v[166:169], v[202:205], v[32:35]
	v_mfma_f32_16x16x32_bf16 v[24:27], v[186:189], v[202:205], v[24:27]
	v_mfma_f32_16x16x32_bf16 v[16:19], v[166:169], v[210:213], v[16:19]
	v_mfma_f32_16x16x32_bf16 v[8:11], v[186:189], v[210:213], v[8:11]
	v_mfma_f32_16x16x32_bf16 v[4:7], v[166:169], v[218:221], v[4:7]
	v_mfma_f32_16x16x32_bf16 v[0:3], v[186:189], v[218:221], v[0:3]
	s_setprio 0
	s_barrier
	s_add_i32 s72, 0, 0x18000
	s_add_i32 s73, 0, 0x1c000
	v_add_u32_e32 v156, s72, v141
	v_add_u32_e32 v181, s73, v141
	ds_read_b128 v[144:147], v156
	ds_read_b128 v[148:151], v156 offset:1024
	ds_read_b128 v[152:155], v156 offset:2048
	ds_read_b128 v[156:159], v156 offset:3072
	ds_read_b128 v[162:165], v181
	ds_read_b128 v[166:169], v181 offset:1024
	ds_read_b128 v[182:185], v181 offset:2048
	ds_read_b128 v[186:189], v181 offset:3072
	s_add_u32 s44, s44, 0xc0000
	s_addc_u32 s45, s45, 0
	s_mov_b32 m0, s74
	v_lshl_add_u64 v[226:227], s[44:45], 0, v[132:133]
	ds_read_b128 v[190:193], v143 offset:32768
	ds_read_b128 v[194:197], v143 offset:33792
	ds_read_b128 v[198:201], v143 offset:34816
	ds_read_b128 v[202:205], v143 offset:35840
	ds_read_b128 v[206:209], v143 offset:36864
	ds_read_b128 v[210:213], v143 offset:37888
	ds_read_b128 v[214:217], v143 offset:38912
	ds_read_b128 v[218:221], v143 offset:39936
	global_load_lds_dwordx4 v[226:227], off
	v_lshl_add_u64 v[226:227], s[44:45], 0, v[130:131]
	s_mov_b32 m0, s75
	s_nop 0
	global_load_lds_dwordx4 v[226:227], off
	s_waitcnt vmcnt(8)
	s_waitcnt lgkmcnt(0)
	s_barrier
	s_setprio 1
	s_waitcnt lgkmcnt(0)
	v_mfma_f32_16x16x32_bf16 v[124:127], v[144:147], v[190:193], v[124:127]
	v_mfma_f32_16x16x32_bf16 v[120:123], v[152:155], v[190:193], v[120:123]
	v_mfma_f32_16x16x32_bf16 v[116:119], v[144:147], v[198:201], v[116:119]
	v_mfma_f32_16x16x32_bf16 v[108:111], v[152:155], v[198:201], v[108:111]
	v_mfma_f32_16x16x32_bf16 v[100:103], v[144:147], v[206:209], v[100:103]
	v_mfma_f32_16x16x32_bf16 v[92:95], v[152:155], v[206:209], v[92:95]
	v_mfma_f32_16x16x32_bf16 v[84:87], v[144:147], v[214:217], v[84:87]
	v_mfma_f32_16x16x32_bf16 v[76:79], v[152:155], v[214:217], v[76:79]
	v_mfma_f32_16x16x32_bf16 v[124:127], v[148:151], v[194:197], v[124:127]
	v_mfma_f32_16x16x32_bf16 v[120:123], v[156:159], v[194:197], v[120:123]
	v_mfma_f32_16x16x32_bf16 v[116:119], v[148:151], v[202:205], v[116:119]
	v_mfma_f32_16x16x32_bf16 v[108:111], v[156:159], v[202:205], v[108:111]
	v_mfma_f32_16x16x32_bf16 v[100:103], v[148:151], v[210:213], v[100:103]
	v_mfma_f32_16x16x32_bf16 v[92:95], v[156:159], v[210:213], v[92:95]
	v_mfma_f32_16x16x32_bf16 v[84:87], v[148:151], v[218:221], v[84:87]
	v_mfma_f32_16x16x32_bf16 v[76:79], v[156:159], v[218:221], v[76:79]
	s_setprio 0
	s_setprio 1
	v_mfma_f32_16x16x32_bf16 v[112:115], v[162:165], v[190:193], v[112:115]
	v_mfma_f32_16x16x32_bf16 v[104:107], v[182:185], v[190:193], v[104:107]
	v_mfma_f32_16x16x32_bf16 v[96:99], v[162:165], v[198:201], v[96:99]
	v_mfma_f32_16x16x32_bf16 v[88:91], v[182:185], v[198:201], v[88:91]
	v_mfma_f32_16x16x32_bf16 v[80:83], v[162:165], v[206:209], v[80:83]
	v_mfma_f32_16x16x32_bf16 v[72:75], v[182:185], v[206:209], v[72:75]
	v_mfma_f32_16x16x32_bf16 v[68:71], v[162:165], v[214:217], v[68:71]
	v_mfma_f32_16x16x32_bf16 v[64:67], v[182:185], v[214:217], v[64:67]
	v_mfma_f32_16x16x32_bf16 v[112:115], v[166:169], v[194:197], v[112:115]
	v_mfma_f32_16x16x32_bf16 v[104:107], v[186:189], v[194:197], v[104:107]
	v_mfma_f32_16x16x32_bf16 v[96:99], v[166:169], v[202:205], v[96:99]
	v_mfma_f32_16x16x32_bf16 v[88:91], v[186:189], v[202:205], v[88:91]
	v_mfma_f32_16x16x32_bf16 v[80:83], v[166:169], v[210:213], v[80:83]
	v_mfma_f32_16x16x32_bf16 v[72:75], v[186:189], v[210:213], v[72:75]
	v_mfma_f32_16x16x32_bf16 v[68:71], v[166:169], v[218:221], v[68:71]
	v_mfma_f32_16x16x32_bf16 v[64:67], v[186:189], v[218:221], v[64:67]
	s_setprio 0
	s_barrier
	s_add_i32 s44, s72, s61
	v_lshl_add_u64 v[138:139], v[138:139], 0, s[64:65]
	s_mov_b32 m0, s44
	ds_read_b128 v[190:193], v143 offset:49152
	ds_read_b128 v[194:197], v143 offset:50176
	ds_read_b128 v[198:201], v143 offset:51200
	ds_read_b128 v[202:205], v143 offset:52224
	ds_read_b128 v[206:209], v143 offset:53248
	ds_read_b128 v[210:213], v143 offset:54272
	ds_read_b128 v[214:217], v143 offset:55296
	ds_read_b128 v[218:221], v143 offset:56320
	global_load_lds_dwordx4 v[138:139], off
	s_add_i32 m0, s44, 0x2000
	s_add_u32 s20, s20, 0x20080
	v_lshl_add_u64 v[138:139], v[170:171], 0, s[64:65]
	s_addc_u32 s21, s21, 0
	s_add_i32 s44, s73, s61
	global_load_lds_dwordx4 v[138:139], off
	v_lshl_add_u64 v[138:139], s[20:21], 0, v[160:161]
	s_mov_b32 m0, s44
	s_nop 0
	global_load_lds_dwordx4 v[138:139], off
	v_lshl_add_u64 v[138:139], s[20:21], 0, v[128:129]
	s_add_i32 m0, s44, 0x2000
	s_nop 0
	global_load_lds_dwordx4 v[138:139], off
	v_lshl_add_u64 v[138:139], v[222:223], 0, s[64:65]
	s_mov_b32 m0, s76
	s_nop 0
	global_load_lds_dwordx4 v[138:139], off
	v_lshl_add_u64 v[138:139], v[224:225], 0, s[64:65]
	s_mov_b32 m0, s77
	s_nop 0
	global_load_lds_dwordx4 v[138:139], off
	s_waitcnt vmcnt(8)
	s_waitcnt lgkmcnt(0)
	s_barrier
	s_setprio 1
	s_waitcnt lgkmcnt(0)
	v_mfma_f32_16x16x32_bf16 v[60:63], v[144:147], v[190:193], v[60:63]
	v_mfma_f32_16x16x32_bf16 v[56:59], v[152:155], v[190:193], v[56:59]
	v_mfma_f32_16x16x32_bf16 v[52:55], v[144:147], v[198:201], v[52:55]
	v_mfma_f32_16x16x32_bf16 v[44:47], v[152:155], v[198:201], v[44:47]
	v_mfma_f32_16x16x32_bf16 v[36:39], v[144:147], v[206:209], v[36:39]
	v_mfma_f32_16x16x32_bf16 v[28:31], v[152:155], v[206:209], v[28:31]
	v_mfma_f32_16x16x32_bf16 v[20:23], v[144:147], v[214:217], v[20:23]
	v_mfma_f32_16x16x32_bf16 v[12:15], v[152:155], v[214:217], v[12:15]
	v_mfma_f32_16x16x32_bf16 v[60:63], v[148:151], v[194:197], v[60:63]
	v_mfma_f32_16x16x32_bf16 v[56:59], v[156:159], v[194:197], v[56:59]
	v_mfma_f32_16x16x32_bf16 v[52:55], v[148:151], v[202:205], v[52:55]
	v_mfma_f32_16x16x32_bf16 v[44:47], v[156:159], v[202:205], v[44:47]
	v_mfma_f32_16x16x32_bf16 v[36:39], v[148:151], v[210:213], v[36:39]
	v_mfma_f32_16x16x32_bf16 v[28:31], v[156:159], v[210:213], v[28:31]
	v_mfma_f32_16x16x32_bf16 v[20:23], v[148:151], v[218:221], v[20:23]
	v_mfma_f32_16x16x32_bf16 v[12:15], v[156:159], v[218:221], v[12:15]
	s_setprio 0
	s_setprio 1
	v_mfma_f32_16x16x32_bf16 v[48:51], v[162:165], v[190:193], v[48:51]
	v_mfma_f32_16x16x32_bf16 v[40:43], v[182:185], v[190:193], v[40:43]
	v_mfma_f32_16x16x32_bf16 v[32:35], v[162:165], v[198:201], v[32:35]
	v_mfma_f32_16x16x32_bf16 v[24:27], v[182:185], v[198:201], v[24:27]
	v_mfma_f32_16x16x32_bf16 v[16:19], v[162:165], v[206:209], v[16:19]
	v_mfma_f32_16x16x32_bf16 v[8:11], v[182:185], v[206:209], v[8:11]
	v_mfma_f32_16x16x32_bf16 v[4:7], v[162:165], v[214:217], v[4:7]
	v_mfma_f32_16x16x32_bf16 v[0:3], v[182:185], v[214:217], v[0:3]
	v_mfma_f32_16x16x32_bf16 v[48:51], v[166:169], v[194:197], v[48:51]
	v_mfma_f32_16x16x32_bf16 v[40:43], v[186:189], v[194:197], v[40:43]
	v_mfma_f32_16x16x32_bf16 v[32:35], v[166:169], v[202:205], v[32:35]
	v_mfma_f32_16x16x32_bf16 v[24:27], v[186:189], v[202:205], v[24:27]
	v_mfma_f32_16x16x32_bf16 v[16:19], v[166:169], v[210:213], v[16:19]
	v_mfma_f32_16x16x32_bf16 v[8:11], v[186:189], v[210:213], v[8:11]
	v_mfma_f32_16x16x32_bf16 v[4:7], v[166:169], v[218:221], v[4:7]
	v_mfma_f32_16x16x32_bf16 v[0:3], v[186:189], v[218:221], v[0:3]
	s_setprio 0
	s_barrier
	s_add_i32 s82, s82, 2
	s_add_u32 s80, s80, 0x100
	s_addc_u32 s81, s81, 0
	s_mov_b32 s95, 0
	s_cmp_gt_u32 s82, 5
	s_mov_b64 s[72:73], s[18:19]
	s_cbranch_scc0 .LBB0_471
	s_branch .Lst_qk_after

.Lst_qk_after:
	s_and_b64 vcc, exec, s[12:13]
	s_cbranch_vccz .LBB0_474
	s_barrier

.LBB0_1136:
	v_lshrrev_b32_e32 v16, 1, v3
	v_lshl_add_u64 v[8:9], s[12:13], 0, v[160:161]
	v_mov_b32_e32 v129, v161
	v_and_b32_e32 v16, 24, v16
	s_lshl_b32 s0, s0, 5
	v_lshl_add_u64 v[10:11], s[12:13], 0, v[128:129]
	v_mov_b32_e32 v133, v161
	v_and_b32_e32 v7, 15, v3
	v_lshlrev_b32_e32 v17, 1, v16
	v_lshlrev_b32_e32 v3, 2, v3
	s_and_b32 s7, s0, 0x60
	s_add_i32 m0, s58, 0x18000
	v_lshl_add_u64 v[8:9], v[8:9], 0, s[64:65]
	v_lshl_add_u64 v[12:13], s[16:17], 0, v[132:133]
	v_mov_b32_e32 v131, v161
	v_lshl_or_b32 v140, s1, 6, v7
	v_lshl_or_b32 v7, v7, 6, v17
	s_lshl_b32 s1, s1, 13
	v_and_b32_e32 v3, 32, v3
	s_lshl_b32 s0, s7, 7
	s_waitcnt vmcnt(2)
	s_barrier
	global_load_lds_dwordx4 v[8:9], off
	v_lshl_add_u64 v[8:9], v[10:11], 0, s[64:65]
	s_add_i32 m0, s58, 0x1a000
	s_add_i32 s62, s58, 0x8000
	s_add_i32 s63, s58, 0xa000
	v_lshl_add_u64 v[14:15], s[16:17], 0, v[130:131]
	v_bitop3_b32 v141, v7, s0, v3 bitop3:0xde
	global_load_lds_dwordx4 v[8:9], off
	v_lshl_add_u64 v[8:9], v[12:13], 0, s[64:65]
	s_mov_b32 m0, s62
	s_add_u32 s0, s12, 0x80080
	v_bitop3_b32 v17, v7, s1, v3 bitop3:0xde
	global_load_lds_dwordx4 v[8:9], off
	v_lshl_add_u64 v[8:9], v[14:15], 0, s[64:65]
	s_mov_b32 m0, s63
	s_addc_u32 s1, s13, 0
	global_load_lds_dwordx4 v[8:9], off
	s_add_i32 m0, s58, 0x1c000
	v_lshl_add_u64 v[8:9], s[0:1], 0, v[160:161]
	global_load_lds_dwordx4 v[8:9], off
	v_lshl_add_u64 v[8:9], s[0:1], 0, v[128:129]
	s_add_i32 m0, s58, 0x1e000
	v_lshlrev_b32_e32 v3, 15, v5
	global_load_lds_dwordx4 v[8:9], off
	v_and_b32_e32 v3, 0xffff0000, v3
	v_lshl_add_u32 v3, v4, 12, v3
	v_and_b32_e32 v4, 1, v5
	v_lshl_or_b32 v3, v4, 6, v3
	v_lshl_add_u32 v134, v6, 1, v3
	v_lshlrev_b32_e32 v3, 15, v0
	v_and_b32_e32 v3, 0xffff0000, v3
	s_waitcnt vmcnt(6)
	v_lshl_add_u32 v1, v1, 12, v3
	v_and_b32_e32 v0, 1, v0
	s_cmpk_lt_u32 s18, 0x100
	v_lshl_or_b32 v0, v0, 6, v1
	s_cselect_b64 s[22:23], -1, 0
	v_or_b32_e32 v142, s7, v16
	v_mov_b32_e32 v135, v161
	v_lshl_add_u32 v136, v2, 1, v0
	v_mov_b32_e32 v137, v161
	s_mov_b32 s66, 0
	v_add_u32_e32 v143, 0, v17
	s_barrier
	s_mov_b32 s95, 0
	s_branch .LBB0_1139

.LBB0_1140:
	s_add_u32 s18, s54, 0xfff80080
	s_addc_u32 s19, s55, -1
	s_add_i32 s73, 0, 0x10000
	s_cmp_eq_u32 s72, 28
	s_cselect_b32 s21, s9, s19
	s_cselect_b32 s20, s67, s18
	v_add_u32_e32 v138, s73, v141
	s_cselect_b32 s19, s7, s71
	s_cselect_b32 s18, s68, s70
	s_add_i32 s76, 0, 0x14000
	ds_read_b128 v[144:147], v138
	ds_read_b128 v[148:151], v138 offset:1024
	ds_read_b128 v[152:155], v138 offset:2048
	ds_read_b128 v[156:159], v138 offset:3072
	v_add_u32_e32 v138, s76, v141
	ds_read_b128 v[162:165], v138
	ds_read_b128 v[166:169], v138 offset:1024
	ds_read_b128 v[182:185], v138 offset:2048
	ds_read_b128 v[186:189], v138 offset:3072
	v_lshl_add_u64 v[138:139], s[54:55], 0, v[134:135]
	s_add_i32 m0, s58, 0xc000
	ds_read_b128 v[190:193], v143
	ds_read_b128 v[194:197], v143 offset:1024
	ds_read_b128 v[198:201], v143 offset:2048
	ds_read_b128 v[202:205], v143 offset:3072
	ds_read_b128 v[206:209], v143 offset:4096
	ds_read_b128 v[210:213], v143 offset:5120
	ds_read_b128 v[214:217], v143 offset:6144
	ds_read_b128 v[218:221], v143 offset:7168
	global_load_lds_dwordx4 v[138:139], off
	v_lshl_add_u64 v[138:139], s[54:55], 0, v[136:137]
	s_add_i32 m0, s58, 0xe000
	s_nop 0
	global_load_lds_dwordx4 v[138:139], off
	s_cmp_lg_u32 s95, 0
	s_cbranch_scc1 .Lst_mu_r0
	s_waitcnt vmcnt(8)
.Lst_mu_d0:
	s_waitcnt lgkmcnt(0)
	s_barrier
	s_setprio 1
	s_waitcnt lgkmcnt(0)
	v_mfma_f32_16x16x32_bf16 v[124:127], v[144:147], v[190:193], v[124:127]
	v_mfma_f32_16x16x32_bf16 v[120:123], v[152:155], v[190:193], v[120:123]
	v_mfma_f32_16x16x32_bf16 v[108:111], v[144:147], v[198:201], v[108:111]
	v_mfma_f32_16x16x32_bf16 v[104:107], v[152:155], v[198:201], v[104:107]
	v_mfma_f32_16x16x32_bf16 v[92:95], v[144:147], v[206:209], v[92:95]
	v_mfma_f32_16x16x32_bf16 v[88:91], v[152:155], v[206:209], v[88:91]
	v_mfma_f32_16x16x32_bf16 v[76:79], v[144:147], v[214:217], v[76:79]
	v_mfma_f32_16x16x32_bf16 v[72:75], v[152:155], v[214:217], v[72:75]
	v_mfma_f32_16x16x32_bf16 v[124:127], v[148:151], v[194:197], v[124:127]
	v_mfma_f32_16x16x32_bf16 v[120:123], v[156:159], v[194:197], v[120:123]
	v_mfma_f32_16x16x32_bf16 v[108:111], v[148:151], v[202:205], v[108:111]
	v_mfma_f32_16x16x32_bf16 v[104:107], v[156:159], v[202:205], v[104:107]
	v_mfma_f32_16x16x32_bf16 v[92:95], v[148:151], v[210:213], v[92:95]
	v_mfma_f32_16x16x32_bf16 v[88:91], v[156:159], v[210:213], v[88:91]
	v_mfma_f32_16x16x32_bf16 v[76:79], v[148:151], v[218:221], v[76:79]
	v_mfma_f32_16x16x32_bf16 v[72:75], v[156:159], v[218:221], v[72:75]
	s_setprio 0
	s_setprio 1
	v_mfma_f32_16x16x32_bf16 v[116:119], v[162:165], v[190:193], v[116:119]
	v_mfma_f32_16x16x32_bf16 v[112:115], v[182:185], v[190:193], v[112:115]
	v_mfma_f32_16x16x32_bf16 v[100:103], v[162:165], v[198:201], v[100:103]
	v_mfma_f32_16x16x32_bf16 v[96:99], v[182:185], v[198:201], v[96:99]
	v_mfma_f32_16x16x32_bf16 v[84:87], v[162:165], v[206:209], v[84:87]
	v_mfma_f32_16x16x32_bf16 v[80:83], v[182:185], v[206:209], v[80:83]
	v_mfma_f32_16x16x32_bf16 v[68:71], v[162:165], v[214:217], v[68:71]
	v_mfma_f32_16x16x32_bf16 v[64:67], v[182:185], v[214:217], v[64:67]
	v_mfma_f32_16x16x32_bf16 v[116:119], v[166:169], v[194:197], v[116:119]
	v_mfma_f32_16x16x32_bf16 v[112:115], v[186:189], v[194:197], v[112:115]
	v_mfma_f32_16x16x32_bf16 v[100:103], v[166:169], v[202:205], v[100:103]
	v_mfma_f32_16x16x32_bf16 v[96:99], v[186:189], v[202:205], v[96:99]
	v_mfma_f32_16x16x32_bf16 v[84:87], v[166:169], v[210:213], v[84:87]
	v_mfma_f32_16x16x32_bf16 v[80:83], v[186:189], v[210:213], v[80:83]
	v_mfma_f32_16x16x32_bf16 v[68:71], v[166:169], v[218:221], v[68:71]
	v_mfma_f32_16x16x32_bf16 v[64:67], v[186:189], v[218:221], v[64:67]
	s_setprio 0
	s_barrier
	s_add_i32 s73, s73, s51
	v_lshl_add_u64 v[138:139], s[18:19], 0, v[160:161]
	s_mov_b32 m0, s73
	ds_read_b128 v[190:193], v143 offset:16384
	ds_read_b128 v[194:197], v143 offset:17408
	ds_read_b128 v[198:201], v143 offset:18432
	ds_read_b128 v[202:205], v143 offset:19456
	ds_read_b128 v[206:209], v143 offset:20480
	ds_read_b128 v[210:213], v143 offset:21504
	ds_read_b128 v[214:217], v143 offset:22528
	ds_read_b128 v[218:221], v143 offset:23552
	global_load_lds_dwordx4 v[138:139], off
	s_add_i32 m0, s73, 0x2000
	s_add_u32 s74, s18, 0x80000
	v_lshl_add_u64 v[170:171], s[18:19], 0, v[128:129]
	s_addc_u32 s75, s19, 0
	s_add_i32 s73, s76, s51
	global_load_lds_dwordx4 v[170:171], off
	v_lshl_add_u64 v[222:223], s[74:75], 0, v[160:161]
	s_mov_b32 m0, s73
	v_lshl_add_u64 v[224:225], s[20:21], 0, v[130:131]
	global_load_lds_dwordx4 v[222:223], off
	v_lshl_add_u64 v[222:223], s[74:75], 0, v[128:129]
	s_add_i32 m0, s73, 0x2000
	s_nop 0
	global_load_lds_dwordx4 v[222:223], off
	v_lshl_add_u64 v[222:223], s[20:21], 0, v[132:133]
	s_mov_b32 m0, s58
	s_nop 0
	global_load_lds_dwordx4 v[222:223], off
	s_mov_b32 m0, s59
	s_nop 0
	global_load_lds_dwordx4 v[224:225], off
	s_cmp_lg_u32 s95, 0
	s_cbranch_scc1 .Lst_mu_r1
	s_waitcnt vmcnt(8)
.Lst_mu_d1:
	s_waitcnt lgkmcnt(0)
	s_barrier
	s_setprio 1
	s_waitcnt lgkmcnt(0)
	v_mfma_f32_16x16x32_bf16 v[60:63], v[144:147], v[190:193], v[60:63]
	v_mfma_f32_16x16x32_bf16 v[56:59], v[152:155], v[190:193], v[56:59]
	v_mfma_f32_16x16x32_bf16 v[44:47], v[144:147], v[198:201], v[44:47]
	v_mfma_f32_16x16x32_bf16 v[40:43], v[152:155], v[198:201], v[40:43]
	v_mfma_f32_16x16x32_bf16 v[28:31], v[144:147], v[206:209], v[28:31]
	v_mfma_f32_16x16x32_bf16 v[24:27], v[152:155], v[206:209], v[24:27]
	v_mfma_f32_16x16x32_bf16 v[12:15], v[144:147], v[214:217], v[12:15]
	v_mfma_f32_16x16x32_bf16 v[8:11], v[152:155], v[214:217], v[8:11]
	v_mfma_f32_16x16x32_bf16 v[60:63], v[148:151], v[194:197], v[60:63]
	v_mfma_f32_16x16x32_bf16 v[56:59], v[156:159], v[194:197], v[56:59]
	v_mfma_f32_16x16x32_bf16 v[44:47], v[148:151], v[202:205], v[44:47]
	v_mfma_f32_16x16x32_bf16 v[40:43], v[156:159], v[202:205], v[40:43]
	v_mfma_f32_16x16x32_bf16 v[28:31], v[148:151], v[210:213], v[28:31]
	v_mfma_f32_16x16x32_bf16 v[24:27], v[156:159], v[210:213], v[24:27]
	v_mfma_f32_16x16x32_bf16 v[12:15], v[148:151], v[218:221], v[12:15]
	v_mfma_f32_16x16x32_bf16 v[8:11], v[156:159], v[218:221], v[8:11]
	s_setprio 0
	s_setprio 1
	v_mfma_f32_16x16x32_bf16 v[52:55], v[162:165], v[190:193], v[52:55]
	v_mfma_f32_16x16x32_bf16 v[48:51], v[182:185], v[190:193], v[48:51]
	v_mfma_f32_16x16x32_bf16 v[36:39], v[162:165], v[198:201], v[36:39]
	v_mfma_f32_16x16x32_bf16 v[32:35], v[182:185], v[198:201], v[32:35]
	v_mfma_f32_16x16x32_bf16 v[20:23], v[162:165], v[206:209], v[20:23]
	v_mfma_f32_16x16x32_bf16 v[16:19], v[182:185], v[206:209], v[16:19]
	v_mfma_f32_16x16x32_bf16 v[4:7], v[162:165], v[214:217], v[4:7]
	v_mfma_f32_16x16x32_bf16 v[0:3], v[182:185], v[214:217], v[0:3]
	v_mfma_f32_16x16x32_bf16 v[52:55], v[166:169], v[194:197], v[52:55]
	v_mfma_f32_16x16x32_bf16 v[48:51], v[186:189], v[194:197], v[48:51]
	v_mfma_f32_16x16x32_bf16 v[36:39], v[166:169], v[202:205], v[36:39]
	v_mfma_f32_16x16x32_bf16 v[32:35], v[186:189], v[202:205], v[32:35]
	v_mfma_f32_16x16x32_bf16 v[20:23], v[166:169], v[210:213], v[20:23]
	v_mfma_f32_16x16x32_bf16 v[16:19], v[186:189], v[210:213], v[16:19]
	v_mfma_f32_16x16x32_bf16 v[4:7], v[166:169], v[218:221], v[4:7]
	v_mfma_f32_16x16x32_bf16 v[0:3], v[186:189], v[218:221], v[0:3]
	s_setprio 0
	s_barrier
	s_add_i32 s73, 0, 0x18000
	s_add_i32 s74, 0, 0x1c000
	v_add_u32_e32 v156, s73, v141
	v_add_u32_e32 v181, s74, v141
	ds_read_b128 v[144:147], v156
	ds_read_b128 v[148:151], v156 offset:1024
	ds_read_b128 v[152:155], v156 offset:2048
	ds_read_b128 v[156:159], v156 offset:3072
	ds_read_b128 v[162:165], v181
	ds_read_b128 v[166:169], v181 offset:1024
	ds_read_b128 v[182:185], v181 offset:2048
	ds_read_b128 v[186:189], v181 offset:3072
	s_add_u32 s20, s20, 0x80000
	s_addc_u32 s21, s21, 0
	s_mov_b32 m0, s60
	v_lshl_add_u64 v[226:227], s[20:21], 0, v[132:133]
	ds_read_b128 v[190:193], v143 offset:32768
	ds_read_b128 v[194:197], v143 offset:33792
	ds_read_b128 v[198:201], v143 offset:34816
	ds_read_b128 v[202:205], v143 offset:35840
	ds_read_b128 v[206:209], v143 offset:36864
	ds_read_b128 v[210:213], v143 offset:37888
	ds_read_b128 v[214:217], v143 offset:38912
	ds_read_b128 v[218:221], v143 offset:39936
	global_load_lds_dwordx4 v[226:227], off
	v_lshl_add_u64 v[226:227], s[20:21], 0, v[130:131]
	s_mov_b32 m0, s61
	s_nop 0
	global_load_lds_dwordx4 v[226:227], off
	s_waitcnt vmcnt(8)
	s_waitcnt lgkmcnt(0)
	s_barrier
	s_setprio 1
	s_waitcnt lgkmcnt(0)
	v_mfma_f32_16x16x32_bf16 v[124:127], v[144:147], v[190:193], v[124:127]
	v_mfma_f32_16x16x32_bf16 v[120:123], v[152:155], v[190:193], v[120:123]
	v_mfma_f32_16x16x32_bf16 v[108:111], v[144:147], v[198:201], v[108:111]
	v_mfma_f32_16x16x32_bf16 v[104:107], v[152:155], v[198:201], v[104:107]
	v_mfma_f32_16x16x32_bf16 v[92:95], v[144:147], v[206:209], v[92:95]
	v_mfma_f32_16x16x32_bf16 v[88:91], v[152:155], v[206:209], v[88:91]
	v_mfma_f32_16x16x32_bf16 v[76:79], v[144:147], v[214:217], v[76:79]
	v_mfma_f32_16x16x32_bf16 v[72:75], v[152:155], v[214:217], v[72:75]
	v_mfma_f32_16x16x32_bf16 v[124:127], v[148:151], v[194:197], v[124:127]
	v_mfma_f32_16x16x32_bf16 v[120:123], v[156:159], v[194:197], v[120:123]
	v_mfma_f32_16x16x32_bf16 v[108:111], v[148:151], v[202:205], v[108:111]
	v_mfma_f32_16x16x32_bf16 v[104:107], v[156:159], v[202:205], v[104:107]
	v_mfma_f32_16x16x32_bf16 v[92:95], v[148:151], v[210:213], v[92:95]
	v_mfma_f32_16x16x32_bf16 v[88:91], v[156:159], v[210:213], v[88:91]
	v_mfma_f32_16x16x32_bf16 v[76:79], v[148:151], v[218:221], v[76:79]
	v_mfma_f32_16x16x32_bf16 v[72:75], v[156:159], v[218:221], v[72:75]
	s_setprio 0
	s_setprio 1
	v_mfma_f32_16x16x32_bf16 v[116:119], v[162:165], v[190:193], v[116:119]
	v_mfma_f32_16x16x32_bf16 v[112:115], v[182:185], v[190:193], v[112:115]
	v_mfma_f32_16x16x32_bf16 v[100:103], v[162:165], v[198:201], v[100:103]
	v_mfma_f32_16x16x32_bf16 v[96:99], v[182:185], v[198:201], v[96:99]
	v_mfma_f32_16x16x32_bf16 v[84:87], v[162:165], v[206:209], v[84:87]
	v_mfma_f32_16x16x32_bf16 v[80:83], v[182:185], v[206:209], v[80:83]
	v_mfma_f32_16x16x32_bf16 v[68:71], v[162:165], v[214:217], v[68:71]
	v_mfma_f32_16x16x32_bf16 v[64:67], v[182:185], v[214:217], v[64:67]
	v_mfma_f32_16x16x32_bf16 v[116:119], v[166:169], v[194:197], v[116:119]
	v_mfma_f32_16x16x32_bf16 v[112:115], v[186:189], v[194:197], v[112:115]
	v_mfma_f32_16x16x32_bf16 v[100:103], v[166:169], v[202:205], v[100:103]
	v_mfma_f32_16x16x32_bf16 v[96:99], v[186:189], v[202:205], v[96:99]
	v_mfma_f32_16x16x32_bf16 v[84:87], v[166:169], v[210:213], v[84:87]
	v_mfma_f32_16x16x32_bf16 v[80:83], v[186:189], v[210:213], v[80:83]
	v_mfma_f32_16x16x32_bf16 v[68:71], v[166:169], v[218:221], v[68:71]
	v_mfma_f32_16x16x32_bf16 v[64:67], v[186:189], v[218:221], v[64:67]
	s_setprio 0
	s_barrier
	s_add_i32 s20, s73, s51
	v_lshl_add_u64 v[138:139], v[138:139], 0, s[64:65]
	s_mov_b32 m0, s20
	ds_read_b128 v[190:193], v143 offset:49152
	ds_read_b128 v[194:197], v143 offset:50176
	ds_read_b128 v[198:201], v143 offset:51200
	ds_read_b128 v[202:205], v143 offset:52224
	ds_read_b128 v[206:209], v143 offset:53248
	ds_read_b128 v[210:213], v143 offset:54272
	ds_read_b128 v[214:217], v143 offset:55296
	ds_read_b128 v[218:221], v143 offset:56320
	global_load_lds_dwordx4 v[138:139], off
	s_add_i32 m0, s20, 0x2000
	s_add_u32 s18, s18, 0x80080
	v_lshl_add_u64 v[138:139], v[170:171], 0, s[64:65]
	s_addc_u32 s19, s19, 0
	s_add_i32 s20, s74, s51
	global_load_lds_dwordx4 v[138:139], off
	v_lshl_add_u64 v[138:139], s[18:19], 0, v[160:161]
	s_mov_b32 m0, s20
	s_nop 0
	global_load_lds_dwordx4 v[138:139], off
	v_lshl_add_u64 v[138:139], s[18:19], 0, v[128:129]
	s_add_i32 m0, s20, 0x2000
	s_nop 0
	global_load_lds_dwordx4 v[138:139], off
	v_lshl_add_u64 v[138:139], v[222:223], 0, s[64:65]
	s_mov_b32 m0, s62
	s_nop 0
	global_load_lds_dwordx4 v[138:139], off
	v_lshl_add_u64 v[138:139], v[224:225], 0, s[64:65]
	s_mov_b32 m0, s63
	s_nop 0
	global_load_lds_dwordx4 v[138:139], off
	s_waitcnt vmcnt(8)
	s_waitcnt lgkmcnt(0)
	s_barrier
	s_setprio 1
	s_waitcnt lgkmcnt(0)
	v_mfma_f32_16x16x32_bf16 v[60:63], v[144:147], v[190:193], v[60:63]
	v_mfma_f32_16x16x32_bf16 v[56:59], v[152:155], v[190:193], v[56:59]
	v_mfma_f32_16x16x32_bf16 v[44:47], v[144:147], v[198:201], v[44:47]
	v_mfma_f32_16x16x32_bf16 v[40:43], v[152:155], v[198:201], v[40:43]
	v_mfma_f32_16x16x32_bf16 v[28:31], v[144:147], v[206:209], v[28:31]
	v_mfma_f32_16x16x32_bf16 v[24:27], v[152:155], v[206:209], v[24:27]
	v_mfma_f32_16x16x32_bf16 v[12:15], v[144:147], v[214:217], v[12:15]
	v_mfma_f32_16x16x32_bf16 v[8:11], v[152:155], v[214:217], v[8:11]
	v_mfma_f32_16x16x32_bf16 v[60:63], v[148:151], v[194:197], v[60:63]
	v_mfma_f32_16x16x32_bf16 v[56:59], v[156:159], v[194:197], v[56:59]
	v_mfma_f32_16x16x32_bf16 v[44:47], v[148:151], v[202:205], v[44:47]
	v_mfma_f32_16x16x32_bf16 v[40:43], v[156:159], v[202:205], v[40:43]
	v_mfma_f32_16x16x32_bf16 v[28:31], v[148:151], v[210:213], v[28:31]
	v_mfma_f32_16x16x32_bf16 v[24:27], v[156:159], v[210:213], v[24:27]
	v_mfma_f32_16x16x32_bf16 v[12:15], v[148:151], v[218:221], v[12:15]
	v_mfma_f32_16x16x32_bf16 v[8:11], v[156:159], v[218:221], v[8:11]
	s_setprio 0
	s_setprio 1
	v_mfma_f32_16x16x32_bf16 v[52:55], v[162:165], v[190:193], v[52:55]
	v_mfma_f32_16x16x32_bf16 v[48:51], v[182:185], v[190:193], v[48:51]
	v_mfma_f32_16x16x32_bf16 v[36:39], v[162:165], v[198:201], v[36:39]
	v_mfma_f32_16x16x32_bf16 v[32:35], v[182:185], v[198:201], v[32:35]
	v_mfma_f32_16x16x32_bf16 v[20:23], v[162:165], v[206:209], v[20:23]
	v_mfma_f32_16x16x32_bf16 v[16:19], v[182:185], v[206:209], v[16:19]
	v_mfma_f32_16x16x32_bf16 v[4:7], v[162:165], v[214:217], v[4:7]
	v_mfma_f32_16x16x32_bf16 v[0:3], v[182:185], v[214:217], v[0:3]
	v_mfma_f32_16x16x32_bf16 v[52:55], v[166:169], v[194:197], v[52:55]
	v_mfma_f32_16x16x32_bf16 v[48:51], v[186:189], v[194:197], v[48:51]
	v_mfma_f32_16x16x32_bf16 v[36:39], v[166:169], v[202:205], v[36:39]
	v_mfma_f32_16x16x32_bf16 v[32:35], v[186:189], v[202:205], v[32:35]
	v_mfma_f32_16x16x32_bf16 v[20:23], v[166:169], v[210:213], v[20:23]
	v_mfma_f32_16x16x32_bf16 v[16:19], v[186:189], v[210:213], v[16:19]
	v_mfma_f32_16x16x32_bf16 v[4:7], v[166:169], v[218:221], v[4:7]
	v_mfma_f32_16x16x32_bf16 v[0:3], v[186:189], v[218:221], v[0:3]
	s_setprio 0
	s_barrier
	s_add_i32 s72, s72, 2
	s_add_u32 s54, s54, 0x100
	s_addc_u32 s55, s55, 0
	s_add_u32 s70, s70, 0x100
	s_addc_u32 s71, s71, 0
	s_mov_b32 s95, 0
	s_cmp_gt_u32 s72, 29
	s_cbranch_scc0 .LBB0_1140
	s_branch .Lst_mu_after

.Lst_mu_after:
	s_and_b64 vcc, exec, s[22:23]
	s_cbranch_vccz .LBB0_1143
	s_barrier
